# IP1: GEMM K-loop raises wave priority during the load segments (ds_read + LDS-DMA issue) instead of the MFMA blocks, on top of v082
# baseline (speedup 1.0000x reference)
.LBB0_169:
	s_setprio 1
	s_add_i32 s0, s34, 2
	s_add_u32 s1, s80, 0x80
	s_addc_u32 s35, s81, 0
	s_add_i32 s47, 0, 0x10000
	s_cmp_eq_u32 s68, s34
	s_cselect_b32 s35, s43, s35
	s_cselect_b32 s34, s42, s1
	s_cselect_b32 s67, s87, vcc_hi
	s_cselect_b32 s66, s86, vcc_lo
	s_add_i32 s1, 0, 0x14000
	s_waitcnt lgkmcnt(0)
	ds_read_b128 v[130:133], v206
	ds_read_b128 v[134:137], v206 offset:1024
	ds_read_b128 v[138:141], v206 offset:2048
	ds_read_b128 v[142:145], v206 offset:3072
	ds_read_b128 v[146:149], v207
	ds_read_b128 v[150:153], v207 offset:1024
	ds_read_b128 v[154:157], v207 offset:2048
	ds_read_b128 v[158:161], v207 offset:3072
	s_add_i32 m0, s90, 0xc000
	ds_read_b128 v[162:165], v238
	ds_read_b128 v[166:169], v238 offset:1024
	ds_read_b128 v[170:173], v238 offset:2048
	ds_read_b128 v[174:177], v238 offset:3072
	ds_read_b128 v[178:181], v238 offset:4096
	ds_read_b128 v[182:185], v238 offset:5120
	ds_read_b128 v[198:201], v238 offset:6144
	ds_read_b128 v[202:205], v238 offset:7168
	global_load_lds_dwordx4 v194, s[80:81]
	s_add_i32 m0, s90, 0xe000
	s_nop 0
	global_load_lds_dwordx4 v196, s[80:81]
	s_setprio 0
	s_waitcnt vmcnt(8)
	s_waitcnt lgkmcnt(0)
	s_barrier
	v_mfma_f32_16x16x32_bf16 v[126:129], v[130:133], v[162:165], v[126:129]
	v_mfma_f32_16x16x32_bf16 v[122:125], v[138:141], v[162:165], v[122:125]
	v_mfma_f32_16x16x32_bf16 v[118:121], v[130:133], v[170:173], v[118:121]
	v_mfma_f32_16x16x32_bf16 v[102:105], v[138:141], v[170:173], v[102:105]
	v_mfma_f32_16x16x32_bf16 v[94:97], v[130:133], v[178:181], v[94:97]
	v_mfma_f32_16x16x32_bf16 v[90:93], v[138:141], v[178:181], v[90:93]
	v_mfma_f32_16x16x32_bf16 v[78:81], v[130:133], v[198:201], v[78:81]
	v_mfma_f32_16x16x32_bf16 v[74:77], v[138:141], v[198:201], v[74:77]
	v_mfma_f32_16x16x32_bf16 v[126:129], v[134:137], v[166:169], v[126:129]
	v_mfma_f32_16x16x32_bf16 v[122:125], v[142:145], v[166:169], v[122:125]
	v_mfma_f32_16x16x32_bf16 v[118:121], v[134:137], v[174:177], v[118:121]
	v_mfma_f32_16x16x32_bf16 v[102:105], v[142:145], v[174:177], v[102:105]
	v_mfma_f32_16x16x32_bf16 v[94:97], v[134:137], v[182:185], v[94:97]
	v_mfma_f32_16x16x32_bf16 v[90:93], v[142:145], v[182:185], v[90:93]
	v_mfma_f32_16x16x32_bf16 v[78:81], v[134:137], v[202:205], v[78:81]
	v_mfma_f32_16x16x32_bf16 v[74:77], v[142:145], v[202:205], v[74:77]
	v_mfma_f32_16x16x32_bf16 v[114:117], v[146:149], v[162:165], v[114:117]
	v_mfma_f32_16x16x32_bf16 v[110:113], v[154:157], v[162:165], v[110:113]
	v_mfma_f32_16x16x32_bf16 v[106:109], v[146:149], v[170:173], v[106:109]
	v_mfma_f32_16x16x32_bf16 v[98:101], v[154:157], v[170:173], v[98:101]
	v_mfma_f32_16x16x32_bf16 v[86:89], v[146:149], v[178:181], v[86:89]
	v_mfma_f32_16x16x32_bf16 v[82:85], v[154:157], v[178:181], v[82:85]
	v_mfma_f32_16x16x32_bf16 v[70:73], v[146:149], v[198:201], v[70:73]
	v_mfma_f32_16x16x32_bf16 v[66:69], v[154:157], v[198:201], v[66:69]
	v_mfma_f32_16x16x32_bf16 v[114:117], v[150:153], v[166:169], v[114:117]
	v_mfma_f32_16x16x32_bf16 v[110:113], v[158:161], v[166:169], v[110:113]
	v_mfma_f32_16x16x32_bf16 v[106:109], v[150:153], v[174:177], v[106:109]
	v_mfma_f32_16x16x32_bf16 v[98:101], v[158:161], v[174:177], v[98:101]
	v_mfma_f32_16x16x32_bf16 v[86:89], v[150:153], v[182:185], v[86:89]
	v_mfma_f32_16x16x32_bf16 v[82:85], v[158:161], v[182:185], v[82:85]
	v_mfma_f32_16x16x32_bf16 v[70:73], v[150:153], v[202:205], v[70:73]
	v_mfma_f32_16x16x32_bf16 v[66:69], v[158:161], v[202:205], v[66:69]
	s_barrier
	s_setprio 1
	s_add_i32 s47, s47, s57
	s_mov_b32 m0, s47
	ds_read_b128 v[162:165], v238 offset:16384
	ds_read_b128 v[166:169], v238 offset:17408
	ds_read_b128 v[170:173], v238 offset:18432
	ds_read_b128 v[174:177], v238 offset:19456
	ds_read_b128 v[178:181], v238 offset:20480
	ds_read_b128 v[182:185], v238 offset:21504
	ds_read_b128 v[198:201], v238 offset:22528
	ds_read_b128 v[202:205], v238 offset:23552
	global_load_lds_dwordx4 v188, s[66:67]
	s_add_i32 m0, s47, 0x2000
	s_add_u32 s100, s66, s69
	s_addc_u32 s101, s67, 0
	s_add_i32 s1, s1, s57
	global_load_lds_dwordx4 v192, s[66:67]
	s_mov_b32 m0, s1
	s_nop 0
	global_load_lds_dwordx4 v188, s[100:101]
	s_add_i32 m0, s1, 0x2000
	s_nop 0
	global_load_lds_dwordx4 v192, s[100:101]
	s_mov_b32 m0, s90
	s_nop 0
	global_load_lds_dwordx4 v186, s[34:35]
	s_mov_b32 m0, s60
	s_nop 0
	global_load_lds_dwordx4 v190, s[34:35]
	s_setprio 0
	s_waitcnt vmcnt(8)
	s_waitcnt lgkmcnt(0)
	s_barrier
	v_mfma_f32_16x16x32_bf16 v[62:65], v[130:133], v[162:165], v[62:65]
	v_mfma_f32_16x16x32_bf16 v[58:61], v[138:141], v[162:165], v[58:61]
	v_mfma_f32_16x16x32_bf16 v[46:49], v[130:133], v[170:173], v[46:49]
	v_mfma_f32_16x16x32_bf16 v[42:45], v[138:141], v[170:173], v[42:45]
	v_mfma_f32_16x16x32_bf16 v[30:33], v[130:133], v[178:181], v[30:33]
	v_mfma_f32_16x16x32_bf16 v[26:29], v[138:141], v[178:181], v[26:29]
	v_mfma_f32_16x16x32_bf16 v[14:17], v[130:133], v[198:201], v[14:17]
	v_mfma_f32_16x16x32_bf16 v[10:13], v[138:141], v[198:201], v[10:13]
	v_mfma_f32_16x16x32_bf16 v[62:65], v[134:137], v[166:169], v[62:65]
	v_mfma_f32_16x16x32_bf16 v[58:61], v[142:145], v[166:169], v[58:61]
	v_mfma_f32_16x16x32_bf16 v[46:49], v[134:137], v[174:177], v[46:49]
	v_mfma_f32_16x16x32_bf16 v[42:45], v[142:145], v[174:177], v[42:45]
	v_mfma_f32_16x16x32_bf16 v[30:33], v[134:137], v[182:185], v[30:33]
	v_mfma_f32_16x16x32_bf16 v[26:29], v[142:145], v[182:185], v[26:29]
	v_mfma_f32_16x16x32_bf16 v[14:17], v[134:137], v[202:205], v[14:17]
	v_mfma_f32_16x16x32_bf16 v[10:13], v[142:145], v[202:205], v[10:13]
	v_mfma_f32_16x16x32_bf16 v[54:57], v[146:149], v[162:165], v[54:57]
	v_mfma_f32_16x16x32_bf16 v[50:53], v[154:157], v[162:165], v[50:53]
	v_mfma_f32_16x16x32_bf16 v[38:41], v[146:149], v[170:173], v[38:41]
	v_mfma_f32_16x16x32_bf16 v[34:37], v[154:157], v[170:173], v[34:37]
	v_mfma_f32_16x16x32_bf16 v[22:25], v[146:149], v[178:181], v[22:25]
	v_mfma_f32_16x16x32_bf16 v[18:21], v[154:157], v[178:181], v[18:21]
	v_mfma_f32_16x16x32_bf16 v[6:9], v[146:149], v[198:201], v[6:9]
	v_mfma_f32_16x16x32_bf16 v[2:5], v[154:157], v[198:201], v[2:5]
	v_mfma_f32_16x16x32_bf16 v[54:57], v[150:153], v[166:169], v[54:57]
	v_mfma_f32_16x16x32_bf16 v[50:53], v[158:161], v[166:169], v[50:53]
	v_mfma_f32_16x16x32_bf16 v[38:41], v[150:153], v[174:177], v[38:41]
	v_mfma_f32_16x16x32_bf16 v[34:37], v[158:161], v[174:177], v[34:37]
	v_mfma_f32_16x16x32_bf16 v[22:25], v[150:153], v[182:185], v[22:25]
	v_mfma_f32_16x16x32_bf16 v[18:21], v[158:161], v[182:185], v[18:21]
	v_mfma_f32_16x16x32_bf16 v[6:9], v[150:153], v[202:205], v[6:9]
	v_mfma_f32_16x16x32_bf16 v[2:5], v[158:161], v[202:205], v[2:5]
	s_barrier
	s_setprio 1
	s_add_i32 s1, 0, 0x18000
	s_add_i32 s47, 0, 0x1c000
	ds_read_b128 v[130:133], v208
	ds_read_b128 v[134:137], v208 offset:1024
	ds_read_b128 v[138:141], v208 offset:2048
	ds_read_b128 v[142:145], v208 offset:3072
	ds_read_b128 v[146:149], v209
	ds_read_b128 v[150:153], v209 offset:1024
	ds_read_b128 v[154:157], v209 offset:2048
	ds_read_b128 v[158:161], v209 offset:3072
	s_mov_b32 m0, s61
	ds_read_b128 v[162:165], v238 offset:32768
	ds_read_b128 v[166:169], v238 offset:33792
	ds_read_b128 v[170:173], v238 offset:34816
	ds_read_b128 v[174:177], v238 offset:35840
	ds_read_b128 v[178:181], v238 offset:36864
	ds_read_b128 v[182:185], v238 offset:37888
	ds_read_b128 v[198:201], v238 offset:38912
	ds_read_b128 v[202:205], v238 offset:39936
	global_load_lds_dwordx4 v194, s[34:35]
	s_mov_b32 m0, s71
	s_nop 0
	global_load_lds_dwordx4 v196, s[34:35]
	s_setprio 0
	s_waitcnt vmcnt(8)
	s_waitcnt lgkmcnt(0)
	s_barrier
	v_mfma_f32_16x16x32_bf16 v[126:129], v[130:133], v[162:165], v[126:129]
	v_mfma_f32_16x16x32_bf16 v[122:125], v[138:141], v[162:165], v[122:125]
	v_mfma_f32_16x16x32_bf16 v[118:121], v[130:133], v[170:173], v[118:121]
	v_mfma_f32_16x16x32_bf16 v[102:105], v[138:141], v[170:173], v[102:105]
	v_mfma_f32_16x16x32_bf16 v[94:97], v[130:133], v[178:181], v[94:97]
	v_mfma_f32_16x16x32_bf16 v[90:93], v[138:141], v[178:181], v[90:93]
	v_mfma_f32_16x16x32_bf16 v[78:81], v[130:133], v[198:201], v[78:81]
	v_mfma_f32_16x16x32_bf16 v[74:77], v[138:141], v[198:201], v[74:77]
	v_mfma_f32_16x16x32_bf16 v[126:129], v[134:137], v[166:169], v[126:129]
	v_mfma_f32_16x16x32_bf16 v[122:125], v[142:145], v[166:169], v[122:125]
	v_mfma_f32_16x16x32_bf16 v[118:121], v[134:137], v[174:177], v[118:121]
	v_mfma_f32_16x16x32_bf16 v[102:105], v[142:145], v[174:177], v[102:105]
	v_mfma_f32_16x16x32_bf16 v[94:97], v[134:137], v[182:185], v[94:97]
	v_mfma_f32_16x16x32_bf16 v[90:93], v[142:145], v[182:185], v[90:93]
	v_mfma_f32_16x16x32_bf16 v[78:81], v[134:137], v[202:205], v[78:81]
	v_mfma_f32_16x16x32_bf16 v[74:77], v[142:145], v[202:205], v[74:77]
	v_mfma_f32_16x16x32_bf16 v[114:117], v[146:149], v[162:165], v[114:117]
	v_mfma_f32_16x16x32_bf16 v[110:113], v[154:157], v[162:165], v[110:113]
	v_mfma_f32_16x16x32_bf16 v[106:109], v[146:149], v[170:173], v[106:109]
	v_mfma_f32_16x16x32_bf16 v[98:101], v[154:157], v[170:173], v[98:101]
	v_mfma_f32_16x16x32_bf16 v[86:89], v[146:149], v[178:181], v[86:89]
	v_mfma_f32_16x16x32_bf16 v[82:85], v[154:157], v[178:181], v[82:85]
	v_mfma_f32_16x16x32_bf16 v[70:73], v[146:149], v[198:201], v[70:73]
	v_mfma_f32_16x16x32_bf16 v[66:69], v[154:157], v[198:201], v[66:69]
	v_mfma_f32_16x16x32_bf16 v[114:117], v[150:153], v[166:169], v[114:117]
	v_mfma_f32_16x16x32_bf16 v[110:113], v[158:161], v[166:169], v[110:113]
	v_mfma_f32_16x16x32_bf16 v[106:109], v[150:153], v[174:177], v[106:109]
	v_mfma_f32_16x16x32_bf16 v[98:101], v[158:161], v[174:177], v[98:101]
	v_mfma_f32_16x16x32_bf16 v[86:89], v[150:153], v[182:185], v[86:89]
	v_mfma_f32_16x16x32_bf16 v[82:85], v[158:161], v[182:185], v[82:85]
	v_mfma_f32_16x16x32_bf16 v[70:73], v[150:153], v[202:205], v[70:73]
	v_mfma_f32_16x16x32_bf16 v[66:69], v[158:161], v[202:205], v[66:69]
	s_barrier
	s_setprio 1
	s_add_i32 s1, s1, s57
	s_add_u32 s66, s66, 0x80
	s_addc_u32 s67, s67, 0
	s_add_u32 s100, s100, 0x80
	s_addc_u32 s101, s101, 0
	s_add_u32 s34, s34, 0x80
	s_addc_u32 s35, s35, 0
	s_mov_b32 m0, s1
	ds_read_b128 v[162:165], v238 offset:49152
	ds_read_b128 v[166:169], v238 offset:50176
	ds_read_b128 v[170:173], v238 offset:51200
	ds_read_b128 v[174:177], v238 offset:52224
	ds_read_b128 v[178:181], v238 offset:53248
	ds_read_b128 v[182:185], v238 offset:54272
	ds_read_b128 v[198:201], v238 offset:55296
	ds_read_b128 v[202:205], v238 offset:56320
	global_load_lds_dwordx4 v188, s[66:67]
	s_add_i32 m0, s1, 0x2000
	s_add_i32 s1, s47, s57
	global_load_lds_dwordx4 v192, s[66:67]
	s_mov_b32 m0, s1
	s_nop 0
	global_load_lds_dwordx4 v188, s[100:101]
	s_add_i32 m0, s1, 0x2000
	s_nop 0
	global_load_lds_dwordx4 v192, s[100:101]
	s_mov_b32 m0, s64
	s_nop 0
	global_load_lds_dwordx4 v186, s[34:35]
	s_mov_b32 m0, s65
	s_nop 0
	global_load_lds_dwordx4 v190, s[34:35]
	s_setprio 0
	s_waitcnt vmcnt(8)
	s_waitcnt lgkmcnt(0)
	s_barrier
	v_mfma_f32_16x16x32_bf16 v[62:65], v[130:133], v[162:165], v[62:65]
	v_mfma_f32_16x16x32_bf16 v[58:61], v[138:141], v[162:165], v[58:61]
	v_mfma_f32_16x16x32_bf16 v[46:49], v[130:133], v[170:173], v[46:49]
	v_mfma_f32_16x16x32_bf16 v[42:45], v[138:141], v[170:173], v[42:45]
	v_mfma_f32_16x16x32_bf16 v[30:33], v[130:133], v[178:181], v[30:33]
	v_mfma_f32_16x16x32_bf16 v[26:29], v[138:141], v[178:181], v[26:29]
	v_mfma_f32_16x16x32_bf16 v[14:17], v[130:133], v[198:201], v[14:17]
	v_mfma_f32_16x16x32_bf16 v[10:13], v[138:141], v[198:201], v[10:13]
	v_mfma_f32_16x16x32_bf16 v[62:65], v[134:137], v[166:169], v[62:65]
	v_mfma_f32_16x16x32_bf16 v[58:61], v[142:145], v[166:169], v[58:61]
	v_mfma_f32_16x16x32_bf16 v[46:49], v[134:137], v[174:177], v[46:49]
	v_mfma_f32_16x16x32_bf16 v[42:45], v[142:145], v[174:177], v[42:45]
	v_mfma_f32_16x16x32_bf16 v[30:33], v[134:137], v[182:185], v[30:33]
	v_mfma_f32_16x16x32_bf16 v[26:29], v[142:145], v[182:185], v[26:29]
	v_mfma_f32_16x16x32_bf16 v[14:17], v[134:137], v[202:205], v[14:17]
	v_mfma_f32_16x16x32_bf16 v[10:13], v[142:145], v[202:205], v[10:13]
	v_mfma_f32_16x16x32_bf16 v[54:57], v[146:149], v[162:165], v[54:57]
	v_mfma_f32_16x16x32_bf16 v[50:53], v[154:157], v[162:165], v[50:53]
	v_mfma_f32_16x16x32_bf16 v[38:41], v[146:149], v[170:173], v[38:41]
	v_mfma_f32_16x16x32_bf16 v[34:37], v[154:157], v[170:173], v[34:37]
	v_mfma_f32_16x16x32_bf16 v[22:25], v[146:149], v[178:181], v[22:25]
	v_mfma_f32_16x16x32_bf16 v[18:21], v[154:157], v[178:181], v[18:21]
	v_mfma_f32_16x16x32_bf16 v[6:9], v[146:149], v[198:201], v[6:9]
	v_mfma_f32_16x16x32_bf16 v[2:5], v[154:157], v[198:201], v[2:5]
	v_mfma_f32_16x16x32_bf16 v[54:57], v[150:153], v[166:169], v[54:57]
	v_mfma_f32_16x16x32_bf16 v[50:53], v[158:161], v[166:169], v[50:53]
	v_mfma_f32_16x16x32_bf16 v[38:41], v[150:153], v[174:177], v[38:41]
	v_mfma_f32_16x16x32_bf16 v[34:37], v[158:161], v[174:177], v[34:37]
	v_mfma_f32_16x16x32_bf16 v[22:25], v[150:153], v[182:185], v[22:25]
	v_mfma_f32_16x16x32_bf16 v[18:21], v[158:161], v[182:185], v[18:21]
	v_mfma_f32_16x16x32_bf16 v[6:9], v[150:153], v[202:205], v[6:9]
	v_mfma_f32_16x16x32_bf16 v[2:5], v[158:161], v[202:205], v[2:5]
	s_barrier
	s_setprio 1
	s_add_u32 s80, s80, 0x100
	s_addc_u32 s81, s81, 0
	s_add_u32 vcc_lo, vcc_lo, 0x100
	s_addc_u32 vcc_hi, vcc_hi, 0
	s_cmp_ge_u32 s0, s91
	s_mov_b32 s34, s0
	s_cbranch_scc0 .LBB0_169
	s_setprio 0
	v_readlane_b32 s0, v243, 28
	v_readlane_b32 s1, v243, 29
	s_and_b64 vcc, exec, s[0:1]
	s_cbranch_vccz .LBB0_174
	s_barrier
	v_lshl_add_u32 v198, s99, 8, v1
	s_cmp_lt_i32 s70, 1
	s_mov_b64 s[34:35], -1
	s_cbranch_scc0 .LBB0_175
